# YA GEMM epilogue: all 16 gate loads issued up front, per-chunk counted wait (no store drain)
# speedup vs baseline: 1.0025x; 1.0025x over previous
; __device__ __forceinline__ unsigned cvt_pk_bf16(float lo, float hi) { unsigned r; asm volatile("v_cvt_pk_bf16_f32 %0, %1, %2" : "=v"(r) : "v"(lo), "v"(hi)); return r; }
; #define EGAS __attribute__((address_space(1)))
; __device__ __forceinline__ void st8(EGAS bf16_t* dst, f32x4 v0, f32x4 v1) {
;     u32x4 w; w.x = cvt_pk_bf16(v0[0], v0[1]); w.y = cvt_pk_bf16(v0[2], v0[3]); w.z = cvt_pk_bf16(v1[0], v1[1]); w.w = cvt_pk_bf16(v1[2], v1[3]); *(EGAS u32x4*)dst = w; }
; __device__ __forceinline__ void st8nt(EGAS bf16_t* dst, f32x4 v0, f32x4 v1) {
;     u32x4 w; w.x = cvt_pk_bf16(v0[0], v0[1]); w.y = cvt_pk_bf16(v0[2], v0[3]); w.z = cvt_pk_bf16(v1[0], v1[1]); w.w = cvt_pk_bf16(v1[2], v1[3]); __builtin_nontemporal_store(w, (EGAS u32x4*)dst); }
; __device__ __forceinline__ void st8f8(EGAS unsigned char* dst, f32x4 v0, f32x4 v1) {
;     int w0 = __builtin_amdgcn_cvt_pk_fp8_f32(v0[0], v0[1], 0, false); w0 = __builtin_amdgcn_cvt_pk_fp8_f32(v0[2], v0[3], w0, true);
;     int w1 = __builtin_amdgcn_cvt_pk_fp8_f32(v1[0], v1[1], 0, false); w1 = __builtin_amdgcn_cvt_pk_fp8_f32(v1[2], v1[3], w1, true);
;     *(EGAS u32x2e*)dst = (u32x2e){(unsigned)w0, (unsigned)w1}; }
; __device__ __forceinline__ void ld8f8(const EGAS unsigned char* src, f32x4& v0, f32x4& v1) {
;     typedef float f32x2g __attribute__((ext_vector_type(2)));
;     const u32x2e w = *(const EGAS u32x2e*)src;
;     const f32x2g a = __builtin_amdgcn_cvt_pk_f32_fp8((int)w.x, false), b = __builtin_amdgcn_cvt_pk_f32_fp8((int)w.x, true), c = __builtin_amdgcn_cvt_pk_f32_fp8((int)w.y, false), d = __builtin_amdgcn_cvt_pk_f32_fp8((int)w.y, true);
;     v0 = (f32x4){a.x, a.y, b.x, b.y}; v1 = (f32x4){c.x, c.y, d.x, d.y}; }
;     __device__ __forceinline__ void operator()(const f32x4 (&acc)[2][2][4][2], const Unit& u, int wr, int wc, int fr, int fq) const {
;     ...
;                     } else if constexpr (MODE == EP_YA) {
;                         const int c = pn * 256 + ct; f32x4 g0, g1; ld8f8(WS8(WS_GATES) + row * 4096 + c, g0, g1);
;                         st8(WSB(WS_T) + row * 2048 + c, v0 * g0, v1 * g1);
.LBB0_1372:
	v_lshl_add_u32 v150, s24, 8, v146
	v_lshl_or_b32 v144, s25, 8, v148
	v_lshlrev_b32_e32 v0, 12, v150
	v_lshl_add_u64 v[142:143], s[12:13], 0, v[0:1]
	v_ashrrev_i32_e32 v145, 31, v144
	v_lshl_add_u64 v[152:153], v[142:143], 0, v[144:145]
	v_lshl_add_u32 v240, v150, 12, v144
	global_load_dwordx2 v[208:209], v240, s[12:13]
	global_load_dwordx2 v[210:211], v240, s[12:13] offset:128
	v_add_u32_e32 v241, 0x10000, v240
	global_load_dwordx2 v[212:213], v241, s[12:13]
	global_load_dwordx2 v[214:215], v241, s[12:13] offset:128
	v_add_u32_e32 v241, 0x20000, v240
	global_load_dwordx2 v[216:217], v241, s[12:13]
	global_load_dwordx2 v[218:219], v241, s[12:13] offset:128
	v_add_u32_e32 v241, 0x30000, v240
	global_load_dwordx2 v[220:221], v241, s[12:13]
	global_load_dwordx2 v[222:223], v241, s[12:13] offset:128
	v_add_u32_e32 v241, 0x80000, v240
	global_load_dwordx2 v[224:225], v241, s[12:13]
	global_load_dwordx2 v[226:227], v241, s[12:13] offset:128
	v_add_u32_e32 v241, 0x90000, v240
	global_load_dwordx2 v[228:229], v241, s[12:13]
	global_load_dwordx2 v[230:231], v241, s[12:13] offset:128
	v_add_u32_e32 v241, 0xa0000, v240
	global_load_dwordx2 v[232:233], v241, s[12:13]
	global_load_dwordx2 v[234:235], v241, s[12:13] offset:128
	v_add_u32_e32 v241, 0xb0000, v240
	global_load_dwordx2 v[236:237], v241, s[12:13]
	global_load_dwordx2 v[238:239], v241, s[12:13] offset:128
	v_mov_b32_e32 v143, v1
	v_lshlrev_b32_e32 v142, 11, v150
	v_lshl_add_u64 v[156:157], v[142:143], 1, s[8:9]
	v_lshlrev_b64 v[142:143], 1, v[144:145]
	v_lshl_add_u64 v[156:157], v[156:157], 0, v[142:143]
	v_or_b32_e32 v151, 16, v150
	v_lshlrev_b32_e32 v0, 12, v151
	s_andn2_b64 vcc, exec, s[40:41]
	s_mov_b64 s[24:25], -1
	s_waitcnt vmcnt(15)
	v_cvt_pk_f32_fp8_sdwa v[158:159], v208 src0_sel:WORD_1
	v_cvt_pk_f32_fp8_e32 v[160:161], v208
	v_cvt_pk_f32_fp8_sdwa v[162:163], v209 src0_sel:WORD_1
	v_cvt_pk_f32_fp8_e32 v[154:155], v209
	v_pk_mul_f32 v[128:129], v[128:129], v[158:159]
	v_pk_mul_f32 v[126:127], v[126:127], v[160:161]
	v_pk_mul_f32 v[158:159], v[124:125], v[162:163]
	v_pk_mul_f32 v[124:125], v[122:123], v[154:155]
	v_cvt_pk_bf16_f32 v122, v126, v127
	v_cvt_pk_bf16_f32 v123, v128, v129
	s_nop 0
	v_cvt_pk_bf16_f32 v124, v124, v125
	v_cvt_pk_bf16_f32 v125, v158, v159
	global_store_dwordx4 v[156:157], v[122:125], off
	s_waitcnt vmcnt(15)
	v_cvt_pk_f32_fp8_sdwa v[126:127], v210 src0_sel:WORD_1
	v_cvt_pk_f32_fp8_e32 v[128:129], v210
	v_cvt_pk_f32_fp8_sdwa v[152:153], v211 src0_sel:WORD_1
	v_cvt_pk_f32_fp8_e32 v[122:123], v211
	v_lshl_add_u64 v[124:125], s[12:13], 0, v[0:1]
	v_pk_mul_f32 v[120:121], v[120:121], v[126:127]
	v_pk_mul_f32 v[126:127], v[112:113], v[152:153]
	v_pk_mul_f32 v[112:113], v[110:111], v[122:123]
	v_lshl_add_u64 v[124:125], v[124:125], 0, v[144:145]
	v_pk_mul_f32 v[118:119], v[118:119], v[128:129]
	s_nop 0
	v_cvt_pk_bf16_f32 v110, v118, v119
	v_cvt_pk_bf16_f32 v111, v120, v121
	v_cvt_pk_bf16_f32 v112, v112, v113
	v_cvt_pk_bf16_f32 v113, v126, v127
	global_store_dwordx4 v[156:157], v[110:113], off offset:256
	s_waitcnt vmcnt(15)
	v_cvt_pk_f32_fp8_sdwa v[118:119], v212 src0_sel:WORD_1
	v_cvt_pk_f32_fp8_e32 v[120:121], v212
	v_cvt_pk_f32_fp8_sdwa v[122:123], v213 src0_sel:WORD_1
	v_cvt_pk_f32_fp8_e32 v[110:111], v213
	v_mov_b32_e32 v113, v1
	v_lshlrev_b32_e32 v112, 11, v151
	v_lshl_add_u64 v[112:113], v[112:113], 1, s[8:9]
	v_lshl_add_u64 v[112:113], v[112:113], 0, v[142:143]
	v_pk_mul_f32 v[116:117], v[116:117], v[118:119]
	v_pk_mul_f32 v[118:119], v[108:109], v[122:123]
	v_pk_mul_f32 v[108:109], v[106:107], v[110:111]
	v_pk_mul_f32 v[114:115], v[114:115], v[120:121]
	s_nop 0
	v_cvt_pk_bf16_f32 v106, v114, v115
	v_cvt_pk_bf16_f32 v107, v116, v117
	v_cvt_pk_bf16_f32 v108, v108, v109
	v_cvt_pk_bf16_f32 v109, v118, v119
	global_store_dwordx4 v[112:113], v[106:109], off
	v_or_b32_e32 v118, 32, v150
	v_lshlrev_b32_e32 v0, 12, v118
	v_lshl_add_u64 v[108:109], s[12:13], 0, v[0:1]
	v_lshl_add_u64 v[108:109], v[108:109], 0, v[144:145]
	s_waitcnt vmcnt(15)
	v_cvt_pk_f32_fp8_sdwa v[110:111], v214 src0_sel:WORD_1
	v_cvt_pk_f32_fp8_e32 v[114:115], v214
	v_cvt_pk_f32_fp8_sdwa v[116:117], v215 src0_sel:WORD_1
	v_cvt_pk_f32_fp8_e32 v[106:107], v215
	v_pk_mul_f32 v[104:105], v[104:105], v[110:111]
	v_pk_mul_f32 v[102:103], v[102:103], v[114:115]
	v_pk_mul_f32 v[110:111], v[96:97], v[116:117]
	v_pk_mul_f32 v[96:97], v[94:95], v[106:107]
	v_cvt_pk_bf16_f32 v94, v102, v103
	v_cvt_pk_bf16_f32 v95, v104, v105
	s_nop 0
	v_cvt_pk_bf16_f32 v96, v96, v97
	v_cvt_pk_bf16_f32 v97, v110, v111
	global_store_dwordx4 v[112:113], v[94:97], off offset:256
	s_waitcnt vmcnt(15)
	v_cvt_pk_f32_fp8_sdwa v[102:103], v216 src0_sel:WORD_1
	v_cvt_pk_f32_fp8_e32 v[104:105], v216
	v_cvt_pk_f32_fp8_sdwa v[106:107], v217 src0_sel:WORD_1
	v_cvt_pk_f32_fp8_e32 v[94:95], v217
	v_mov_b32_e32 v97, v1
	v_lshlrev_b32_e32 v96, 11, v118
	v_lshl_add_u64 v[96:97], v[96:97], 1, s[8:9]
	v_lshl_add_u64 v[96:97], v[96:97], 0, v[142:143]
	v_pk_mul_f32 v[100:101], v[100:101], v[102:103]
	v_pk_mul_f32 v[102:103], v[92:93], v[106:107]
	v_pk_mul_f32 v[92:93], v[90:91], v[94:95]
	v_pk_mul_f32 v[98:99], v[98:99], v[104:105]
	s_nop 0
	v_cvt_pk_bf16_f32 v90, v98, v99
	v_cvt_pk_bf16_f32 v91, v100, v101
	v_cvt_pk_bf16_f32 v92, v92, v93
	v_cvt_pk_bf16_f32 v93, v102, v103
	global_store_dwordx4 v[96:97], v[90:93], off
	v_or_b32_e32 v102, 48, v150
	v_lshlrev_b32_e32 v0, 12, v102
	v_lshl_add_u64 v[92:93], s[12:13], 0, v[0:1]
	v_lshl_add_u64 v[92:93], v[92:93], 0, v[144:145]
	s_waitcnt vmcnt(15)
; __device__ __forceinline__ unsigned cvt_pk_bf16(float lo, float hi) { unsigned r; asm volatile("v_cvt_pk_bf16_f32 %0, %1, %2" : "=v"(r) : "v"(lo), "v"(hi)); return r; }
; #define EGAS __attribute__((address_space(1)))
; __device__ __forceinline__ void st8(EGAS bf16_t* dst, f32x4 v0, f32x4 v1) {
;     u32x4 w; w.x = cvt_pk_bf16(v0[0], v0[1]); w.y = cvt_pk_bf16(v0[2], v0[3]); w.z = cvt_pk_bf16(v1[0], v1[1]); w.w = cvt_pk_bf16(v1[2], v1[3]); *(EGAS u32x4*)dst = w; }
; __device__ __forceinline__ void st8nt(EGAS bf16_t* dst, f32x4 v0, f32x4 v1) {
;     u32x4 w; w.x = cvt_pk_bf16(v0[0], v0[1]); w.y = cvt_pk_bf16(v0[2], v0[3]); w.z = cvt_pk_bf16(v1[0], v1[1]); w.w = cvt_pk_bf16(v1[2], v1[3]); __builtin_nontemporal_store(w, (EGAS u32x4*)dst); }
; __device__ __forceinline__ void st8f8(EGAS unsigned char* dst, f32x4 v0, f32x4 v1) {
;     int w0 = __builtin_amdgcn_cvt_pk_fp8_f32(v0[0], v0[1], 0, false); w0 = __builtin_amdgcn_cvt_pk_fp8_f32(v0[2], v0[3], w0, true);
;     int w1 = __builtin_amdgcn_cvt_pk_fp8_f32(v1[0], v1[1], 0, false); w1 = __builtin_amdgcn_cvt_pk_fp8_f32(v1[2], v1[3], w1, true);
;     *(EGAS u32x2e*)dst = (u32x2e){(unsigned)w0, (unsigned)w1}; }
; __device__ __forceinline__ void ld8f8(const EGAS unsigned char* src, f32x4& v0, f32x4& v1) {
;     typedef float f32x2g __attribute__((ext_vector_type(2)));
;     const u32x2e w = *(const EGAS u32x2e*)src;
;     const f32x2g a = __builtin_amdgcn_cvt_pk_f32_fp8((int)w.x, false), b = __builtin_amdgcn_cvt_pk_f32_fp8((int)w.x, true), c = __builtin_amdgcn_cvt_pk_f32_fp8((int)w.y, false), d = __builtin_amdgcn_cvt_pk_f32_fp8((int)w.y, true);
;     v0 = (f32x4){a.x, a.y, b.x, b.y}; v1 = (f32x4){c.x, c.y, d.x, d.y}; }
;     __device__ __forceinline__ void operator()(const f32x4 (&acc)[2][2][4][2], const Unit& u, int wr, int wc, int fr, int fq) const {
;     ...
;                     } else if constexpr (MODE == EP_YA) {
;                         const int c = pn * 256 + ct; f32x4 g0, g1; ld8f8(WS8(WS_GATES) + row * 4096 + c, g0, g1);
;                         st8(WSB(WS_T) + row * 2048 + c, v0 * g0, v1 * g1);
	v_cvt_pk_f32_fp8_sdwa v[94:95], v218 src0_sel:WORD_1
	v_cvt_pk_f32_fp8_e32 v[98:99], v218
	v_cvt_pk_f32_fp8_sdwa v[100:101], v219 src0_sel:WORD_1
	v_cvt_pk_f32_fp8_e32 v[90:91], v219
	v_pk_mul_f32 v[88:89], v[88:89], v[94:95]
	v_pk_mul_f32 v[86:87], v[86:87], v[98:99]
	v_pk_mul_f32 v[94:95], v[80:81], v[100:101]
	v_pk_mul_f32 v[80:81], v[78:79], v[90:91]
	v_cvt_pk_bf16_f32 v78, v86, v87
	v_cvt_pk_bf16_f32 v79, v88, v89
	s_nop 0
	v_cvt_pk_bf16_f32 v80, v80, v81
	v_cvt_pk_bf16_f32 v81, v94, v95
	global_store_dwordx4 v[96:97], v[78:81], off offset:256
	s_waitcnt vmcnt(15)
	v_cvt_pk_f32_fp8_sdwa v[86:87], v220 src0_sel:WORD_1
	v_cvt_pk_f32_fp8_e32 v[88:89], v220
	v_cvt_pk_f32_fp8_sdwa v[90:91], v221 src0_sel:WORD_1
	v_cvt_pk_f32_fp8_e32 v[78:79], v221
	v_mov_b32_e32 v81, v1
	v_lshlrev_b32_e32 v80, 11, v102
	v_lshl_add_u64 v[80:81], v[80:81], 1, s[8:9]
	v_lshl_add_u64 v[80:81], v[80:81], 0, v[142:143]
	v_pk_mul_f32 v[84:85], v[84:85], v[86:87]
	v_pk_mul_f32 v[86:87], v[76:77], v[90:91]
	v_pk_mul_f32 v[76:77], v[74:75], v[78:79]
	v_pk_mul_f32 v[82:83], v[82:83], v[88:89]
	s_nop 0
	v_cvt_pk_bf16_f32 v74, v82, v83
	v_cvt_pk_bf16_f32 v75, v84, v85
	v_cvt_pk_bf16_f32 v76, v76, v77
	v_cvt_pk_bf16_f32 v77, v86, v87
	global_store_dwordx4 v[80:81], v[74:77], off
	v_add_u32_e32 v86, 0x80, v150
	v_lshlrev_b32_e32 v0, 12, v86
	v_lshl_add_u64 v[76:77], s[12:13], 0, v[0:1]
	v_lshl_add_u64 v[76:77], v[76:77], 0, v[144:145]
	s_waitcnt vmcnt(15)
	v_cvt_pk_f32_fp8_sdwa v[78:79], v222 src0_sel:WORD_1
	v_cvt_pk_f32_fp8_e32 v[82:83], v222
	v_cvt_pk_f32_fp8_sdwa v[84:85], v223 src0_sel:WORD_1
	v_cvt_pk_f32_fp8_e32 v[74:75], v223
	v_pk_mul_f32 v[72:73], v[72:73], v[78:79]
	v_pk_mul_f32 v[70:71], v[70:71], v[82:83]
	v_pk_mul_f32 v[78:79], v[68:69], v[84:85]
	v_pk_mul_f32 v[68:69], v[66:67], v[74:75]
	v_cvt_pk_bf16_f32 v66, v70, v71
	v_cvt_pk_bf16_f32 v67, v72, v73
	s_nop 0
	v_cvt_pk_bf16_f32 v68, v68, v69
	v_cvt_pk_bf16_f32 v69, v78, v79
	global_store_dwordx4 v[80:81], v[66:69], off offset:256
	s_waitcnt vmcnt(15)
	v_cvt_pk_f32_fp8_sdwa v[70:71], v224 src0_sel:WORD_1
	v_cvt_pk_f32_fp8_e32 v[72:73], v224
	v_cvt_pk_f32_fp8_sdwa v[74:75], v225 src0_sel:WORD_1
	v_cvt_pk_f32_fp8_e32 v[66:67], v225
	v_mov_b32_e32 v69, v1
	v_lshlrev_b32_e32 v68, 11, v86
	v_lshl_add_u64 v[68:69], v[68:69], 1, s[8:9]
	v_lshl_add_u64 v[68:69], v[68:69], 0, v[142:143]
	v_pk_mul_f32 v[64:65], v[64:65], v[70:71]
	v_pk_mul_f32 v[70:71], v[60:61], v[74:75]
	v_pk_mul_f32 v[60:61], v[58:59], v[66:67]
	v_pk_mul_f32 v[62:63], v[62:63], v[72:73]
	s_nop 0
	v_cvt_pk_bf16_f32 v58, v62, v63
	v_cvt_pk_bf16_f32 v59, v64, v65
	v_cvt_pk_bf16_f32 v60, v60, v61
	v_cvt_pk_bf16_f32 v61, v70, v71
	global_store_dwordx4 v[68:69], v[58:61], off
	v_add_u32_e32 v70, 0x90, v150
	v_lshlrev_b32_e32 v0, 12, v70
	v_lshl_add_u64 v[60:61], s[12:13], 0, v[0:1]
	v_lshl_add_u64 v[60:61], v[60:61], 0, v[144:145]
	s_waitcnt vmcnt(15)
	v_cvt_pk_f32_fp8_sdwa v[62:63], v226 src0_sel:WORD_1
	v_cvt_pk_f32_fp8_e32 v[64:65], v226
	v_cvt_pk_f32_fp8_sdwa v[66:67], v227 src0_sel:WORD_1
	v_cvt_pk_f32_fp8_e32 v[58:59], v227
	v_pk_mul_f32 v[56:57], v[56:57], v[62:63]
	v_pk_mul_f32 v[54:55], v[54:55], v[64:65]
	v_pk_mul_f32 v[62:63], v[48:49], v[66:67]
	v_pk_mul_f32 v[48:49], v[46:47], v[58:59]
	v_cvt_pk_bf16_f32 v46, v54, v55
	v_cvt_pk_bf16_f32 v47, v56, v57
	s_nop 0
	v_cvt_pk_bf16_f32 v48, v48, v49
	v_cvt_pk_bf16_f32 v49, v62, v63
	global_store_dwordx4 v[68:69], v[46:49], off offset:256
	s_waitcnt vmcnt(15)
; __device__ __forceinline__ unsigned cvt_pk_bf16(float lo, float hi) { unsigned r; asm volatile("v_cvt_pk_bf16_f32 %0, %1, %2" : "=v"(r) : "v"(lo), "v"(hi)); return r; }
; #define EGAS __attribute__((address_space(1)))
; __device__ __forceinline__ void st8(EGAS bf16_t* dst, f32x4 v0, f32x4 v1) {
;     u32x4 w; w.x = cvt_pk_bf16(v0[0], v0[1]); w.y = cvt_pk_bf16(v0[2], v0[3]); w.z = cvt_pk_bf16(v1[0], v1[1]); w.w = cvt_pk_bf16(v1[2], v1[3]); *(EGAS u32x4*)dst = w; }
; __device__ __forceinline__ void st8nt(EGAS bf16_t* dst, f32x4 v0, f32x4 v1) {
;     u32x4 w; w.x = cvt_pk_bf16(v0[0], v0[1]); w.y = cvt_pk_bf16(v0[2], v0[3]); w.z = cvt_pk_bf16(v1[0], v1[1]); w.w = cvt_pk_bf16(v1[2], v1[3]); __builtin_nontemporal_store(w, (EGAS u32x4*)dst); }
; __device__ __forceinline__ void st8f8(EGAS unsigned char* dst, f32x4 v0, f32x4 v1) {
;     int w0 = __builtin_amdgcn_cvt_pk_fp8_f32(v0[0], v0[1], 0, false); w0 = __builtin_amdgcn_cvt_pk_fp8_f32(v0[2], v0[3], w0, true);
;     int w1 = __builtin_amdgcn_cvt_pk_fp8_f32(v1[0], v1[1], 0, false); w1 = __builtin_amdgcn_cvt_pk_fp8_f32(v1[2], v1[3], w1, true);
;     *(EGAS u32x2e*)dst = (u32x2e){(unsigned)w0, (unsigned)w1}; }
; __device__ __forceinline__ void ld8f8(const EGAS unsigned char* src, f32x4& v0, f32x4& v1) {
;     typedef float f32x2g __attribute__((ext_vector_type(2)));
;     const u32x2e w = *(const EGAS u32x2e*)src;
;     const f32x2g a = __builtin_amdgcn_cvt_pk_f32_fp8((int)w.x, false), b = __builtin_amdgcn_cvt_pk_f32_fp8((int)w.x, true), c = __builtin_amdgcn_cvt_pk_f32_fp8((int)w.y, false), d = __builtin_amdgcn_cvt_pk_f32_fp8((int)w.y, true);
;     v0 = (f32x4){a.x, a.y, b.x, b.y}; v1 = (f32x4){c.x, c.y, d.x, d.y}; }
;     __device__ __forceinline__ void operator()(const f32x4 (&acc)[2][2][4][2], const Unit& u, int wr, int wc, int fr, int fq) const {
;     ...
;                     } else if constexpr (MODE == EP_YA) {
;                         const int c = pn * 256 + ct; f32x4 g0, g1; ld8f8(WS8(WS_GATES) + row * 4096 + c, g0, g1);
;                         st8(WSB(WS_T) + row * 2048 + c, v0 * g0, v1 * g1);
	v_cvt_pk_f32_fp8_sdwa v[54:55], v228 src0_sel:WORD_1
	v_cvt_pk_f32_fp8_e32 v[56:57], v228
	v_cvt_pk_f32_fp8_sdwa v[58:59], v229 src0_sel:WORD_1
	v_cvt_pk_f32_fp8_e32 v[46:47], v229
	v_mov_b32_e32 v49, v1
	v_lshlrev_b32_e32 v48, 11, v70
	v_lshl_add_u64 v[48:49], v[48:49], 1, s[8:9]
	v_lshl_add_u64 v[48:49], v[48:49], 0, v[142:143]
	v_pk_mul_f32 v[52:53], v[52:53], v[54:55]
	v_pk_mul_f32 v[54:55], v[44:45], v[58:59]
	v_pk_mul_f32 v[44:45], v[42:43], v[46:47]
	v_pk_mul_f32 v[50:51], v[50:51], v[56:57]
	s_nop 0
	v_cvt_pk_bf16_f32 v42, v50, v51
	v_cvt_pk_bf16_f32 v43, v52, v53
	v_cvt_pk_bf16_f32 v44, v44, v45
	v_cvt_pk_bf16_f32 v45, v54, v55
	global_store_dwordx4 v[48:49], v[42:45], off
	v_add_u32_e32 v54, 0xa0, v150
	v_lshlrev_b32_e32 v0, 12, v54
	v_lshl_add_u64 v[44:45], s[12:13], 0, v[0:1]
	v_lshl_add_u64 v[44:45], v[44:45], 0, v[144:145]
	s_waitcnt vmcnt(15)
	v_cvt_pk_f32_fp8_sdwa v[46:47], v230 src0_sel:WORD_1
	v_cvt_pk_f32_fp8_e32 v[50:51], v230
	v_cvt_pk_f32_fp8_sdwa v[52:53], v231 src0_sel:WORD_1
	v_cvt_pk_f32_fp8_e32 v[42:43], v231
	v_pk_mul_f32 v[40:41], v[40:41], v[46:47]
	v_pk_mul_f32 v[38:39], v[38:39], v[50:51]
	v_pk_mul_f32 v[46:47], v[32:33], v[52:53]
	v_pk_mul_f32 v[32:33], v[30:31], v[42:43]
	v_cvt_pk_bf16_f32 v30, v38, v39
	v_cvt_pk_bf16_f32 v31, v40, v41
	s_nop 0
	v_cvt_pk_bf16_f32 v32, v32, v33
	v_cvt_pk_bf16_f32 v33, v46, v47
	global_store_dwordx4 v[48:49], v[30:33], off offset:256
	s_waitcnt vmcnt(15)
	v_cvt_pk_f32_fp8_sdwa v[38:39], v232 src0_sel:WORD_1
	v_cvt_pk_f32_fp8_e32 v[40:41], v232
	v_cvt_pk_f32_fp8_sdwa v[42:43], v233 src0_sel:WORD_1
	v_cvt_pk_f32_fp8_e32 v[30:31], v233
	v_mov_b32_e32 v33, v1
	v_lshlrev_b32_e32 v32, 11, v54
	v_lshl_add_u64 v[32:33], v[32:33], 1, s[8:9]
	v_lshl_add_u64 v[32:33], v[32:33], 0, v[142:143]
	v_pk_mul_f32 v[36:37], v[36:37], v[38:39]
	v_pk_mul_f32 v[38:39], v[28:29], v[42:43]
	v_pk_mul_f32 v[28:29], v[26:27], v[30:31]
	v_pk_mul_f32 v[34:35], v[34:35], v[40:41]
	s_nop 0
	v_cvt_pk_bf16_f32 v26, v34, v35
	v_cvt_pk_bf16_f32 v27, v36, v37
	v_cvt_pk_bf16_f32 v28, v28, v29
	v_cvt_pk_bf16_f32 v29, v38, v39
	global_store_dwordx4 v[32:33], v[26:29], off
	v_add_u32_e32 v38, 0xb0, v150
	v_lshlrev_b32_e32 v0, 12, v38
	v_lshl_add_u64 v[28:29], s[12:13], 0, v[0:1]
	v_lshl_add_u64 v[28:29], v[28:29], 0, v[144:145]
	s_waitcnt vmcnt(15)
	v_cvt_pk_f32_fp8_sdwa v[30:31], v234 src0_sel:WORD_1
	v_cvt_pk_f32_fp8_e32 v[34:35], v234
	v_cvt_pk_f32_fp8_sdwa v[36:37], v235 src0_sel:WORD_1
	v_cvt_pk_f32_fp8_e32 v[26:27], v235
	v_pk_mul_f32 v[24:25], v[24:25], v[30:31]
	v_pk_mul_f32 v[22:23], v[22:23], v[34:35]
	v_pk_mul_f32 v[30:31], v[16:17], v[36:37]
	v_pk_mul_f32 v[16:17], v[14:15], v[26:27]
	v_cvt_pk_bf16_f32 v14, v22, v23
	v_cvt_pk_bf16_f32 v15, v24, v25
	s_nop 0
	v_cvt_pk_bf16_f32 v16, v16, v17
	v_cvt_pk_bf16_f32 v17, v30, v31
	global_store_dwordx4 v[32:33], v[14:17], off offset:256
	s_waitcnt vmcnt(15)
	v_cvt_pk_f32_fp8_sdwa v[22:23], v236 src0_sel:WORD_1
	v_cvt_pk_f32_fp8_e32 v[24:25], v236
	v_cvt_pk_f32_fp8_sdwa v[26:27], v237 src0_sel:WORD_1
	v_cvt_pk_f32_fp8_e32 v[14:15], v237
	v_mov_b32_e32 v17, v1
	v_lshlrev_b32_e32 v16, 11, v38
	v_lshl_add_u64 v[16:17], v[16:17], 1, s[8:9]
	v_lshl_add_u64 v[16:17], v[16:17], 0, v[142:143]
	v_pk_mul_f32 v[20:21], v[20:21], v[22:23]
	v_pk_mul_f32 v[22:23], v[12:13], v[26:27]
	v_pk_mul_f32 v[12:13], v[10:11], v[14:15]
	v_pk_mul_f32 v[18:19], v[18:19], v[24:25]
	s_nop 0
	v_cvt_pk_bf16_f32 v10, v18, v19
	v_cvt_pk_bf16_f32 v11, v20, v21
	v_cvt_pk_bf16_f32 v12, v12, v13
	v_cvt_pk_bf16_f32 v13, v22, v23
	global_store_dwordx4 v[16:17], v[10:13], off
	s_waitcnt vmcnt(15)
	v_cvt_pk_f32_fp8_e32 v[14:15], v238
	v_cvt_pk_f32_fp8_sdwa v[12:13], v238 src0_sel:WORD_1
	v_cvt_pk_f32_fp8_sdwa v[18:19], v239 src0_sel:WORD_1
	v_cvt_pk_f32_fp8_e32 v[10:11], v239
	v_pk_mul_f32 v[6:7], v[6:7], v[14:15]
	v_pk_mul_f32 v[8:9], v[8:9], v[12:13]
	v_pk_mul_f32 v[12:13], v[4:5], v[18:19]
	v_pk_mul_f32 v[4:5], v[2:3], v[10:11]
	v_cvt_pk_bf16_f32 v2, v6, v7
	v_cvt_pk_bf16_f32 v3, v8, v9
	s_nop 0
	v_cvt_pk_bf16_f32 v4, v4, v5
	v_cvt_pk_bf16_f32 v5, v12, v13
	global_store_dwordx4 v[16:17], v[2:5], off offset:256
	s_cbranch_vccnz .LBB0_1361
	s_andn2_b64 vcc, exec, s[10:11]
	s_cbranch_vccnz .LBB0_1360
	s_barrier
	s_branch .LBB0_1360
